# E36: squared-ReLU up-GEMM epilogues drop 164 redundant canonicalizing v_max (relu max follows), s_nop 1 keeps store-data WAR spacing
# speedup vs baseline: 1.0012x; 1.0003x over previous
.LBB0_2373:
	s_mov_b32 s19, 0
	s_mov_b32 s21, 0
	s_mov_b32 s52, 0
	s_mov_b32 s53, 0
	v_lshl_add_u32 v150, s42, 8, v144
	v_ashrrev_i32_e32 v151, 31, v150
	v_max_f32_e32 v122, 0, v122
	v_lshlrev_b64 v[154:155], 13, v[150:151]
	v_mul_f32_e32 v151, v122, v122
	v_max_f32_e32 v122, v127, v127
	v_lshl_or_b32 v152, s75, 8, v146
	v_max_f32_e32 v124, 0, v124
	v_max_f32_e32 v120, 0, v120
	v_max_f32_e32 v121, 0, v121
	v_max_f32_e32 v126, 0, v126
	v_max_f32_e32 v122, 0, v122
	v_ashrrev_i32_e32 v153, 31, v152
	v_mul_f32_e32 v124, v124, v124
	v_mul_f32_e32 v120, v120, v120
	v_max_f32_e32 v125, 0, v125
	v_mul_f32_e32 v121, v121, v121
	v_mul_f32_e32 v126, v126, v126
	v_max_f32_e32 v123, 0, v123
	v_mul_f32_e32 v127, v122, v122
	v_mul_f32_e32 v125, v125, v125
	v_mul_f32_e32 v156, v123, v123
	v_cvt_pk_bf16_f32 v122, v124, v125
	v_cvt_pk_bf16_f32 v123, v126, v127
	v_cvt_pk_bf16_f32 v124, v120, v121
	v_lshl_add_u64 v[120:121], s[6:7], 0, v[154:155]
	v_lshlrev_b64 v[126:127], 1, v[152:153]
	v_lshl_add_u64 v[120:121], v[120:121], 0, v[126:127]
	v_max_f32_e32 v112, 0, v112
	v_max_f32_e32 v113, 0, v113
	v_max_f32_e32 v114, 0, v114
	v_cvt_pk_bf16_f32 v125, v151, v156
	global_store_dwordx4 v[120:121], v[122:125], off
	s_nop 1
	v_mul_f32_e32 v122, v112, v112
	v_max_f32_e32 v112, v117, v117
	v_mul_f32_e32 v117, v113, v113
	v_max_f32_e32 v113, v118, v118
	v_mul_f32_e32 v118, v114, v114
	v_max_f32_e32 v114, v119, v119
	v_max_f32_e32 v112, 0, v112
	v_max_f32_e32 v113, 0, v113
	v_max_f32_e32 v114, 0, v114
	v_max_f32_e32 v116, 0, v116
	v_mul_f32_e32 v112, v112, v112
	v_mul_f32_e32 v113, v113, v113
	v_max_f32_e32 v115, 0, v115
	v_mul_f32_e32 v114, v114, v114
	v_mul_f32_e32 v116, v116, v116
	v_mul_f32_e32 v115, v115, v115
	v_cvt_pk_bf16_f32 v112, v116, v112
	v_cvt_pk_bf16_f32 v113, v113, v114
	v_cvt_pk_bf16_f32 v114, v122, v117
	v_max_f32_e32 v104, 0, v104
	v_max_f32_e32 v105, 0, v105
	v_max_f32_e32 v106, 0, v106
	v_cvt_pk_bf16_f32 v115, v118, v115
	global_store_dwordx4 v[120:121], v[112:115], off offset:256
	s_nop 1
	v_max_f32_e32 v108, 0, v108
	v_or_b32_e32 v112, 16, v150
	v_mul_f32_e32 v114, v104, v104
	v_max_f32_e32 v104, v109, v109
	v_mul_f32_e32 v109, v105, v105
	v_max_f32_e32 v105, v110, v110
	v_mul_f32_e32 v110, v106, v106
	v_max_f32_e32 v106, v111, v111
	v_ashrrev_i32_e32 v113, 31, v112
	v_max_f32_e32 v104, 0, v104
	v_max_f32_e32 v105, 0, v105
	v_max_f32_e32 v106, 0, v106
	v_lshlrev_b64 v[112:113], 13, v[112:113]
	v_mul_f32_e32 v108, v108, v108
	v_mul_f32_e32 v104, v104, v104
	v_mul_f32_e32 v105, v105, v105
	v_mul_f32_e32 v106, v106, v106
	v_max_f32_e32 v107, 0, v107
	v_cvt_pk_bf16_f32 v104, v108, v104
	v_cvt_pk_bf16_f32 v105, v105, v106
	v_cvt_pk_bf16_f32 v106, v114, v109
	v_lshl_add_u64 v[108:109], s[6:7], 0, v[112:113]
	v_mul_f32_e32 v107, v107, v107
	v_lshl_add_u64 v[108:109], v[108:109], 0, v[126:127]
	v_max_f32_e32 v96, 0, v96
	v_max_f32_e32 v97, 0, v97
	v_max_f32_e32 v98, 0, v98
	v_cvt_pk_bf16_f32 v107, v110, v107
	global_store_dwordx4 v[108:109], v[104:107], off
	s_nop 1
	v_mul_f32_e32 v104, v96, v96
	v_max_f32_e32 v96, v101, v101
	v_mul_f32_e32 v101, v97, v97
	v_max_f32_e32 v97, v102, v102
	v_mul_f32_e32 v102, v98, v98
	v_max_f32_e32 v98, v103, v103
	v_max_f32_e32 v96, 0, v96
	v_max_f32_e32 v97, 0, v97
	v_max_f32_e32 v98, 0, v98
	v_max_f32_e32 v100, 0, v100
	v_mul_f32_e32 v96, v96, v96
	v_mul_f32_e32 v97, v97, v97
	v_max_f32_e32 v99, 0, v99
	v_mul_f32_e32 v98, v98, v98
	v_mul_f32_e32 v100, v100, v100
	v_mul_f32_e32 v99, v99, v99
	v_cvt_pk_bf16_f32 v96, v100, v96
	v_cvt_pk_bf16_f32 v97, v97, v98
	v_cvt_pk_bf16_f32 v98, v104, v101
	v_max_f32_e32 v88, 0, v88
	v_max_f32_e32 v89, 0, v89
	v_max_f32_e32 v90, 0, v90
	v_cvt_pk_bf16_f32 v99, v102, v99
	global_store_dwordx4 v[108:109], v[96:99], off offset:256
	s_nop 1
	v_max_f32_e32 v92, 0, v92
	v_or_b32_e32 v96, 32, v150
	v_mul_f32_e32 v98, v88, v88
	v_max_f32_e32 v88, v93, v93
	v_mul_f32_e32 v93, v89, v89
	v_max_f32_e32 v89, v94, v94
	v_mul_f32_e32 v94, v90, v90
	v_max_f32_e32 v90, v95, v95
	v_ashrrev_i32_e32 v97, 31, v96
	v_max_f32_e32 v88, 0, v88
	v_max_f32_e32 v89, 0, v89
	v_max_f32_e32 v90, 0, v90
	v_lshlrev_b64 v[96:97], 13, v[96:97]
	v_mul_f32_e32 v92, v92, v92
	v_mul_f32_e32 v88, v88, v88
	v_mul_f32_e32 v89, v89, v89
	v_mul_f32_e32 v90, v90, v90
	v_max_f32_e32 v91, 0, v91
	v_cvt_pk_bf16_f32 v88, v92, v88
	v_cvt_pk_bf16_f32 v89, v89, v90
	v_cvt_pk_bf16_f32 v90, v98, v93
	v_lshl_add_u64 v[92:93], s[6:7], 0, v[96:97]
	v_mul_f32_e32 v91, v91, v91
	v_lshl_add_u64 v[92:93], v[92:93], 0, v[126:127]
	v_max_f32_e32 v80, 0, v80
	v_max_f32_e32 v81, 0, v81
	v_max_f32_e32 v82, 0, v82
	v_cvt_pk_bf16_f32 v91, v94, v91
	global_store_dwordx4 v[92:93], v[88:91], off
	s_nop 1
	v_mul_f32_e32 v88, v80, v80
	v_max_f32_e32 v80, v85, v85
	v_mul_f32_e32 v85, v81, v81
	v_max_f32_e32 v81, v86, v86
	v_mul_f32_e32 v86, v82, v82
	v_max_f32_e32 v82, v87, v87
	v_max_f32_e32 v80, 0, v80
	v_max_f32_e32 v81, 0, v81
	v_max_f32_e32 v82, 0, v82
	v_max_f32_e32 v84, 0, v84
	v_mul_f32_e32 v80, v80, v80
	v_mul_f32_e32 v81, v81, v81
	v_max_f32_e32 v83, 0, v83
	v_mul_f32_e32 v82, v82, v82
	v_mul_f32_e32 v84, v84, v84
	v_mul_f32_e32 v83, v83, v83
	v_cvt_pk_bf16_f32 v80, v84, v80
	v_cvt_pk_bf16_f32 v81, v81, v82
	v_cvt_pk_bf16_f32 v82, v88, v85
	v_max_f32_e32 v72, 0, v72
	v_max_f32_e32 v73, 0, v73
	v_max_f32_e32 v74, 0, v74
	v_cvt_pk_bf16_f32 v83, v86, v83
	global_store_dwordx4 v[92:93], v[80:83], off offset:256
	s_nop 1
	v_max_f32_e32 v76, 0, v76
	v_or_b32_e32 v80, 48, v150
	v_mul_f32_e32 v82, v72, v72
	v_max_f32_e32 v72, v77, v77
	v_mul_f32_e32 v77, v73, v73
	v_max_f32_e32 v73, v78, v78
	v_mul_f32_e32 v78, v74, v74
	v_max_f32_e32 v74, v79, v79
	v_ashrrev_i32_e32 v81, 31, v80
	v_max_f32_e32 v72, 0, v72
	v_max_f32_e32 v73, 0, v73
	v_max_f32_e32 v74, 0, v74
	v_lshlrev_b64 v[80:81], 13, v[80:81]
	v_mul_f32_e32 v76, v76, v76
	v_mul_f32_e32 v72, v72, v72
	v_mul_f32_e32 v73, v73, v73
	v_mul_f32_e32 v74, v74, v74
	v_max_f32_e32 v75, 0, v75
	v_cvt_pk_bf16_f32 v72, v76, v72
	v_cvt_pk_bf16_f32 v73, v73, v74
	v_cvt_pk_bf16_f32 v74, v82, v77
	v_lshl_add_u64 v[76:77], s[6:7], 0, v[80:81]
	v_mul_f32_e32 v75, v75, v75
	v_lshl_add_u64 v[76:77], v[76:77], 0, v[126:127]
	v_max_f32_e32 v64, 0, v64
	v_cvt_pk_bf16_f32 v75, v78, v75
	global_store_dwordx4 v[76:77], v[72:75], off
	v_max_f32_e32 v65, 0, v65
	v_max_f32_e32 v66, 0, v66
	v_mul_f32_e32 v72, v64, v64
	v_max_f32_e32 v64, v69, v69
	v_max_f32_e32 v64, 0, v64
	v_mul_f32_e32 v69, v65, v65
	v_max_f32_e32 v65, v70, v70
	v_mul_f32_e32 v70, v66, v66
	v_max_f32_e32 v66, v71, v71
	v_max_f32_e32 v68, 0, v68
	v_mul_f32_e32 v64, v64, v64
	v_max_f32_e32 v65, 0, v65
	v_max_f32_e32 v66, 0, v66
	v_max_f32_e32 v67, 0, v67
	v_mul_f32_e32 v68, v68, v68
	v_mul_f32_e32 v65, v65, v65
	v_mul_f32_e32 v66, v66, v66
	v_mul_f32_e32 v67, v67, v67
	v_cvt_pk_bf16_f32 v64, v68, v64
	v_max_f32_e32 v56, 0, v56
	v_max_f32_e32 v57, 0, v57
	v_max_f32_e32 v58, 0, v58
	v_cvt_pk_bf16_f32 v65, v65, v66
	v_cvt_pk_bf16_f32 v66, v72, v69
	v_cvt_pk_bf16_f32 v67, v70, v67
	global_store_dwordx4 v[76:77], v[64:67], off offset:256
	s_nop 1
	v_mul_f32_e32 v64, v56, v56
	v_max_f32_e32 v56, v61, v61
	v_mul_f32_e32 v61, v57, v57
	v_max_f32_e32 v57, v62, v62
	v_mul_f32_e32 v62, v58, v58
	v_max_f32_e32 v58, v63, v63
	v_max_f32_e32 v56, 0, v56
	v_max_f32_e32 v57, 0, v57
	v_max_f32_e32 v58, 0, v58
	v_max_f32_e32 v59, 0, v59
	v_max_f32_e32 v60, 0, v60
	v_mul_f32_e32 v56, v56, v56
	v_mul_f32_e32 v57, v57, v57
	v_mul_f32_e32 v58, v58, v58
	v_mul_f32_e32 v59, v59, v59
	s_mov_b32 s19, 0x100000
	v_mul_f32_e32 v60, v60, v60
	v_cvt_pk_bf16_f32 v56, v60, v56
	v_cvt_pk_bf16_f32 v57, v57, v58
	v_cvt_pk_bf16_f32 v58, v64, v61
	v_cvt_pk_bf16_f32 v59, v62, v59
	v_add_co_u32_e32 v62, vcc, s19, v120
	s_nop 0
	v_addc_co_u32_e32 v63, vcc, 0, v121, vcc
	v_max_f32_e32 v48, 0, v48
	global_store_dwordx4 v[62:63], v[56:59], off
	v_max_f32_e32 v49, 0, v49
	v_max_f32_e32 v50, 0, v50
	v_mul_f32_e32 v56, v48, v48
	v_max_f32_e32 v48, v53, v53
	v_max_f32_e32 v48, 0, v48
	v_mul_f32_e32 v53, v49, v49
	v_max_f32_e32 v49, v54, v54
	v_mul_f32_e32 v54, v50, v50
	v_max_f32_e32 v50, v55, v55
	s_mov_b64 s[52:53], 0x100000
	v_max_f32_e32 v52, 0, v52
	v_mul_f32_e32 v48, v48, v48
	v_max_f32_e32 v49, 0, v49
	v_max_f32_e32 v50, 0, v50
	v_max_f32_e32 v51, 0, v51
	v_lshl_add_u64 v[60:61], v[120:121], 0, s[52:53]
	v_mul_f32_e32 v52, v52, v52
	v_mul_f32_e32 v49, v49, v49
	v_mul_f32_e32 v50, v50, v50
	v_mul_f32_e32 v51, v51, v51
	v_cvt_pk_bf16_f32 v48, v52, v48
	v_max_f32_e32 v40, 0, v40
	v_max_f32_e32 v41, 0, v41
	v_max_f32_e32 v42, 0, v42
	v_cvt_pk_bf16_f32 v49, v49, v50
	v_cvt_pk_bf16_f32 v50, v56, v53
	v_cvt_pk_bf16_f32 v51, v54, v51
	global_store_dwordx4 v[60:61], v[48:51], off offset:256
	s_nop 1
	v_mul_f32_e32 v48, v40, v40
	v_max_f32_e32 v40, v45, v45
	v_mul_f32_e32 v45, v41, v41
	v_max_f32_e32 v41, v46, v46
	v_mul_f32_e32 v46, v42, v42
	v_max_f32_e32 v42, v47, v47
	v_max_f32_e32 v40, 0, v40
	v_max_f32_e32 v41, 0, v41
	v_max_f32_e32 v42, 0, v42
	v_max_f32_e32 v43, 0, v43
	v_max_f32_e32 v44, 0, v44
	v_mul_f32_e32 v40, v40, v40
	v_mul_f32_e32 v41, v41, v41
	v_mul_f32_e32 v42, v42, v42
	v_mul_f32_e32 v43, v43, v43
	v_mul_f32_e32 v44, v44, v44
	v_cvt_pk_bf16_f32 v40, v44, v40
	v_cvt_pk_bf16_f32 v41, v41, v42
	v_cvt_pk_bf16_f32 v42, v48, v45
	v_cvt_pk_bf16_f32 v43, v46, v43
	v_add_co_u32_e32 v46, vcc, s72, v120
	s_nop 0
	v_addc_co_u32_e32 v47, vcc, 0, v121, vcc
	v_max_f32_e32 v32, 0, v32
	global_store_dwordx4 v[46:47], v[40:43], off
	v_max_f32_e32 v33, 0, v33
	v_max_f32_e32 v34, 0, v34
	v_mul_f32_e32 v40, v32, v32
	v_max_f32_e32 v32, v37, v37
	v_max_f32_e32 v32, 0, v32
	v_mul_f32_e32 v37, v33, v33
	v_max_f32_e32 v33, v38, v38
	v_mul_f32_e32 v38, v34, v34
	v_max_f32_e32 v34, v39, v39
	v_max_f32_e32 v36, 0, v36
	v_mul_f32_e32 v32, v32, v32
	v_max_f32_e32 v33, 0, v33
	v_max_f32_e32 v34, 0, v34
	v_max_f32_e32 v35, 0, v35
	v_lshl_add_u64 v[44:45], v[120:121], 0, s[12:13]
	v_mul_f32_e32 v36, v36, v36
	v_mul_f32_e32 v33, v33, v33
	v_mul_f32_e32 v34, v34, v34
	v_mul_f32_e32 v35, v35, v35
	v_cvt_pk_bf16_f32 v32, v36, v32
	v_max_f32_e32 v24, 0, v24
	v_max_f32_e32 v25, 0, v25
	v_max_f32_e32 v26, 0, v26
	v_cvt_pk_bf16_f32 v33, v33, v34
	v_cvt_pk_bf16_f32 v34, v40, v37
	v_cvt_pk_bf16_f32 v35, v38, v35
	global_store_dwordx4 v[44:45], v[32:35], off offset:256
	s_nop 1
	v_mul_f32_e32 v32, v24, v24
	v_max_f32_e32 v24, v29, v29
	v_mul_f32_e32 v29, v25, v25
	v_max_f32_e32 v25, v30, v30
	v_mul_f32_e32 v30, v26, v26
	v_max_f32_e32 v26, v31, v31
	v_max_f32_e32 v24, 0, v24
	v_max_f32_e32 v25, 0, v25
	v_max_f32_e32 v26, 0, v26
	v_max_f32_e32 v27, 0, v27
	v_max_f32_e32 v28, 0, v28
	v_mul_f32_e32 v24, v24, v24
	v_mul_f32_e32 v25, v25, v25
	v_mul_f32_e32 v26, v26, v26
	v_mul_f32_e32 v27, v27, v27
	v_mul_f32_e32 v28, v28, v28
	v_cvt_pk_bf16_f32 v24, v28, v24
	v_cvt_pk_bf16_f32 v25, v25, v26
	v_cvt_pk_bf16_f32 v26, v32, v29
	v_cvt_pk_bf16_f32 v27, v30, v27
	v_add_co_u32_e32 v30, vcc, s73, v120
	s_nop 0
	v_addc_co_u32_e32 v31, vcc, 0, v121, vcc
	v_max_f32_e32 v16, 0, v16
	global_store_dwordx4 v[30:31], v[24:27], off
	v_max_f32_e32 v17, 0, v17
	v_max_f32_e32 v18, 0, v18
	v_mul_f32_e32 v24, v16, v16
	v_max_f32_e32 v16, v21, v21
	v_max_f32_e32 v16, 0, v16
	v_mul_f32_e32 v21, v17, v17
	v_max_f32_e32 v17, v22, v22
	v_mul_f32_e32 v22, v18, v18
	v_max_f32_e32 v18, v23, v23
	v_max_f32_e32 v20, 0, v20
	v_mul_f32_e32 v16, v16, v16
	v_max_f32_e32 v17, 0, v17
	v_max_f32_e32 v18, 0, v18
	v_max_f32_e32 v19, 0, v19
	v_lshl_add_u64 v[28:29], v[120:121], 0, s[14:15]
	v_mul_f32_e32 v20, v20, v20
	v_mul_f32_e32 v17, v17, v17
	v_mul_f32_e32 v18, v18, v18
	v_mul_f32_e32 v19, v19, v19
	v_cvt_pk_bf16_f32 v16, v20, v16
	v_max_f32_e32 v8, 0, v8
	v_max_f32_e32 v9, 0, v9
	v_max_f32_e32 v10, 0, v10
	v_cvt_pk_bf16_f32 v17, v17, v18
	v_cvt_pk_bf16_f32 v18, v24, v21
	v_cvt_pk_bf16_f32 v19, v22, v19
	global_store_dwordx4 v[28:29], v[16:19], off offset:256
	s_nop 1
	v_mul_f32_e32 v16, v8, v8
	v_max_f32_e32 v8, v13, v13
	v_mul_f32_e32 v13, v9, v9
	v_max_f32_e32 v9, v14, v14
	v_mul_f32_e32 v14, v10, v10
	v_max_f32_e32 v10, v15, v15
	v_max_f32_e32 v8, 0, v8
	v_max_f32_e32 v9, 0, v9
	v_max_f32_e32 v10, 0, v10
	v_max_f32_e32 v11, 0, v11
	v_max_f32_e32 v12, 0, v12
	v_mul_f32_e32 v8, v8, v8
	v_mul_f32_e32 v9, v9, v9
	v_mul_f32_e32 v10, v10, v10
	v_mul_f32_e32 v11, v11, v11
	v_mul_f32_e32 v12, v12, v12
	v_cvt_pk_bf16_f32 v8, v12, v8
	v_cvt_pk_bf16_f32 v9, v9, v10
	v_cvt_pk_bf16_f32 v10, v16, v13
	v_cvt_pk_bf16_f32 v11, v14, v11
	v_add_co_u32_e32 v14, vcc, s74, v120
	v_addc_co_u32_e32 v15, vcc, 0, v121, vcc
	v_max_f32_e32 v0, 0, v0
	v_max_f32_e32 v1, 0, v1
	v_max_f32_e32 v2, 0, v2
	global_store_dwordx4 v[14:15], v[8:11], off
	s_nop 1
	v_mul_f32_e32 v8, v0, v0
	v_max_f32_e32 v0, v5, v5
	v_mul_f32_e32 v5, v1, v1
	v_max_f32_e32 v1, v6, v6
	v_mul_f32_e32 v6, v2, v2
	v_max_f32_e32 v2, v7, v7
	v_max_f32_e32 v0, 0, v0
	v_max_f32_e32 v1, 0, v1
	v_max_f32_e32 v2, 0, v2
	v_max_f32_e32 v3, 0, v3
	v_lshl_add_u64 v[12:13], v[120:121], 0, s[16:17]
	v_max_f32_e32 v4, 0, v4
	v_mul_f32_e32 v0, v0, v0
	v_mul_f32_e32 v1, v1, v1
	v_mul_f32_e32 v2, v2, v2
	v_mul_f32_e32 v3, v3, v3
	s_andn2_b64 vcc, exec, s[2:3]
	s_mov_b64 s[2:3], -1
	v_mul_f32_e32 v4, v4, v4
	v_cvt_pk_bf16_f32 v0, v4, v0
	v_cvt_pk_bf16_f32 v1, v1, v2
	v_cvt_pk_bf16_f32 v2, v8, v5
	v_cvt_pk_bf16_f32 v3, v6, v3
	global_store_dwordx4 v[12:13], v[0:3], off offset:256
	s_cbranch_vccnz .LBB0_2366
	s_andn2_b64 vcc, exec, s[4:5]
	s_cbranch_vccnz .LBB0_2365
	s_barrier
	s_branch .LBB0_2365

.LBB0_3062:
	s_mov_b32 s21, 0
	s_mov_b32 s23, 0
	s_mov_b32 s54, 0
	s_mov_b32 s55, 0
	v_lshl_add_u32 v150, s52, 8, v144
	v_ashrrev_i32_e32 v151, 31, v150
	v_max_f32_e32 v122, 0, v122
	v_lshlrev_b64 v[154:155], 13, v[150:151]
	v_mul_f32_e32 v151, v122, v122
	v_max_f32_e32 v122, v127, v127
	v_lshl_or_b32 v152, s77, 8, v146
	v_max_f32_e32 v124, 0, v124
	v_max_f32_e32 v120, 0, v120
	v_max_f32_e32 v121, 0, v121
	v_max_f32_e32 v126, 0, v126
	v_max_f32_e32 v122, 0, v122
	v_ashrrev_i32_e32 v153, 31, v152
	v_mul_f32_e32 v124, v124, v124
	v_mul_f32_e32 v120, v120, v120
	v_max_f32_e32 v125, 0, v125
	v_mul_f32_e32 v121, v121, v121
	v_mul_f32_e32 v126, v126, v126
	v_max_f32_e32 v123, 0, v123
	v_mul_f32_e32 v127, v122, v122
	v_mul_f32_e32 v125, v125, v125
	v_mul_f32_e32 v156, v123, v123
	v_cvt_pk_bf16_f32 v122, v124, v125
	v_cvt_pk_bf16_f32 v123, v126, v127
	v_cvt_pk_bf16_f32 v124, v120, v121
	v_lshl_add_u64 v[120:121], s[6:7], 0, v[154:155]
	v_lshlrev_b64 v[126:127], 1, v[152:153]
	v_lshl_add_u64 v[120:121], v[120:121], 0, v[126:127]
	v_max_f32_e32 v112, 0, v112
	v_max_f32_e32 v113, 0, v113
	v_max_f32_e32 v114, 0, v114
	v_cvt_pk_bf16_f32 v125, v151, v156
	global_store_dwordx4 v[120:121], v[122:125], off
	s_nop 1
	v_mul_f32_e32 v122, v112, v112
	v_max_f32_e32 v112, v117, v117
	v_mul_f32_e32 v117, v113, v113
	v_max_f32_e32 v113, v118, v118
	v_mul_f32_e32 v118, v114, v114
	v_max_f32_e32 v114, v119, v119
	v_max_f32_e32 v112, 0, v112
	v_max_f32_e32 v113, 0, v113
	v_max_f32_e32 v114, 0, v114
	v_max_f32_e32 v116, 0, v116
	v_mul_f32_e32 v112, v112, v112
	v_mul_f32_e32 v113, v113, v113
	v_max_f32_e32 v115, 0, v115
	v_mul_f32_e32 v114, v114, v114
	v_mul_f32_e32 v116, v116, v116
	v_mul_f32_e32 v115, v115, v115
	v_cvt_pk_bf16_f32 v112, v116, v112
	v_cvt_pk_bf16_f32 v113, v113, v114
	v_cvt_pk_bf16_f32 v114, v122, v117
	v_max_f32_e32 v104, 0, v104
	v_max_f32_e32 v105, 0, v105
	v_max_f32_e32 v106, 0, v106
	v_cvt_pk_bf16_f32 v115, v118, v115
	global_store_dwordx4 v[120:121], v[112:115], off offset:256
	s_nop 1
	v_max_f32_e32 v108, 0, v108
	v_or_b32_e32 v112, 16, v150
	v_mul_f32_e32 v114, v104, v104
	v_max_f32_e32 v104, v109, v109
	v_mul_f32_e32 v109, v105, v105
	v_max_f32_e32 v105, v110, v110
	v_mul_f32_e32 v110, v106, v106
	v_max_f32_e32 v106, v111, v111
	v_ashrrev_i32_e32 v113, 31, v112
	v_max_f32_e32 v104, 0, v104
	v_max_f32_e32 v105, 0, v105
	v_max_f32_e32 v106, 0, v106
	v_lshlrev_b64 v[112:113], 13, v[112:113]
	v_mul_f32_e32 v108, v108, v108
	v_mul_f32_e32 v104, v104, v104
	v_mul_f32_e32 v105, v105, v105
	v_mul_f32_e32 v106, v106, v106
	v_max_f32_e32 v107, 0, v107
	v_cvt_pk_bf16_f32 v104, v108, v104
	v_cvt_pk_bf16_f32 v105, v105, v106
	v_cvt_pk_bf16_f32 v106, v114, v109
	v_lshl_add_u64 v[108:109], s[6:7], 0, v[112:113]
	v_mul_f32_e32 v107, v107, v107
	v_lshl_add_u64 v[108:109], v[108:109], 0, v[126:127]
	v_max_f32_e32 v96, 0, v96
	v_max_f32_e32 v97, 0, v97
	v_max_f32_e32 v98, 0, v98
	v_cvt_pk_bf16_f32 v107, v110, v107
	global_store_dwordx4 v[108:109], v[104:107], off
	s_nop 1
	v_mul_f32_e32 v104, v96, v96
	v_max_f32_e32 v96, v101, v101
	v_mul_f32_e32 v101, v97, v97
	v_max_f32_e32 v97, v102, v102
	v_mul_f32_e32 v102, v98, v98
	v_max_f32_e32 v98, v103, v103
	v_max_f32_e32 v96, 0, v96
	v_max_f32_e32 v97, 0, v97
	v_max_f32_e32 v98, 0, v98
	v_max_f32_e32 v100, 0, v100
	v_mul_f32_e32 v96, v96, v96
	v_mul_f32_e32 v97, v97, v97
	v_max_f32_e32 v99, 0, v99
	v_mul_f32_e32 v98, v98, v98
	v_mul_f32_e32 v100, v100, v100
	v_mul_f32_e32 v99, v99, v99
	v_cvt_pk_bf16_f32 v96, v100, v96
	v_cvt_pk_bf16_f32 v97, v97, v98
	v_cvt_pk_bf16_f32 v98, v104, v101
	v_max_f32_e32 v88, 0, v88
	v_max_f32_e32 v89, 0, v89
	v_max_f32_e32 v90, 0, v90
	v_cvt_pk_bf16_f32 v99, v102, v99
	global_store_dwordx4 v[108:109], v[96:99], off offset:256
	s_nop 1
	v_max_f32_e32 v92, 0, v92
	v_or_b32_e32 v96, 32, v150
	v_mul_f32_e32 v98, v88, v88
	v_max_f32_e32 v88, v93, v93
	v_mul_f32_e32 v93, v89, v89
	v_max_f32_e32 v89, v94, v94
	v_mul_f32_e32 v94, v90, v90
	v_max_f32_e32 v90, v95, v95
	v_ashrrev_i32_e32 v97, 31, v96
	v_max_f32_e32 v88, 0, v88
	v_max_f32_e32 v89, 0, v89
	v_max_f32_e32 v90, 0, v90
	v_lshlrev_b64 v[96:97], 13, v[96:97]
	v_mul_f32_e32 v92, v92, v92
	v_mul_f32_e32 v88, v88, v88
	v_mul_f32_e32 v89, v89, v89
	v_mul_f32_e32 v90, v90, v90
	v_max_f32_e32 v91, 0, v91
	v_cvt_pk_bf16_f32 v88, v92, v88
	v_cvt_pk_bf16_f32 v89, v89, v90
	v_cvt_pk_bf16_f32 v90, v98, v93
	v_lshl_add_u64 v[92:93], s[6:7], 0, v[96:97]
	v_mul_f32_e32 v91, v91, v91
	v_lshl_add_u64 v[92:93], v[92:93], 0, v[126:127]
	v_max_f32_e32 v80, 0, v80
	v_max_f32_e32 v81, 0, v81
	v_max_f32_e32 v82, 0, v82
	v_cvt_pk_bf16_f32 v91, v94, v91
	global_store_dwordx4 v[92:93], v[88:91], off
	s_nop 1
	v_mul_f32_e32 v88, v80, v80
	v_max_f32_e32 v80, v85, v85
	v_mul_f32_e32 v85, v81, v81
	v_max_f32_e32 v81, v86, v86
	v_mul_f32_e32 v86, v82, v82
	v_max_f32_e32 v82, v87, v87
	v_max_f32_e32 v80, 0, v80
	v_max_f32_e32 v81, 0, v81
	v_max_f32_e32 v82, 0, v82
	v_max_f32_e32 v84, 0, v84
	v_mul_f32_e32 v80, v80, v80
	v_mul_f32_e32 v81, v81, v81
	v_max_f32_e32 v83, 0, v83
	v_mul_f32_e32 v82, v82, v82
	v_mul_f32_e32 v84, v84, v84
	v_mul_f32_e32 v83, v83, v83
	v_cvt_pk_bf16_f32 v80, v84, v80
	v_cvt_pk_bf16_f32 v81, v81, v82
	v_cvt_pk_bf16_f32 v82, v88, v85
	v_max_f32_e32 v72, 0, v72
	v_max_f32_e32 v73, 0, v73
	v_max_f32_e32 v74, 0, v74
	v_cvt_pk_bf16_f32 v83, v86, v83
	global_store_dwordx4 v[92:93], v[80:83], off offset:256
	s_nop 1
	v_max_f32_e32 v76, 0, v76
	v_or_b32_e32 v80, 48, v150
	v_mul_f32_e32 v82, v72, v72
	v_max_f32_e32 v72, v77, v77
	v_mul_f32_e32 v77, v73, v73
	v_max_f32_e32 v73, v78, v78
	v_mul_f32_e32 v78, v74, v74
	v_max_f32_e32 v74, v79, v79
	v_ashrrev_i32_e32 v81, 31, v80
	v_max_f32_e32 v72, 0, v72
	v_max_f32_e32 v73, 0, v73
	v_max_f32_e32 v74, 0, v74
	v_lshlrev_b64 v[80:81], 13, v[80:81]
	v_mul_f32_e32 v76, v76, v76
	v_mul_f32_e32 v72, v72, v72
	v_mul_f32_e32 v73, v73, v73
	v_mul_f32_e32 v74, v74, v74
	v_max_f32_e32 v75, 0, v75
	v_cvt_pk_bf16_f32 v72, v76, v72
	v_cvt_pk_bf16_f32 v73, v73, v74
	v_cvt_pk_bf16_f32 v74, v82, v77
	v_lshl_add_u64 v[76:77], s[6:7], 0, v[80:81]
	v_mul_f32_e32 v75, v75, v75
	v_lshl_add_u64 v[76:77], v[76:77], 0, v[126:127]
	v_max_f32_e32 v64, 0, v64
	v_cvt_pk_bf16_f32 v75, v78, v75
	global_store_dwordx4 v[76:77], v[72:75], off
	v_max_f32_e32 v65, 0, v65
	v_max_f32_e32 v66, 0, v66
	v_mul_f32_e32 v72, v64, v64
	v_max_f32_e32 v64, v69, v69
	v_max_f32_e32 v64, 0, v64
	v_mul_f32_e32 v69, v65, v65
	v_max_f32_e32 v65, v70, v70
	v_mul_f32_e32 v70, v66, v66
	v_max_f32_e32 v66, v71, v71
	v_max_f32_e32 v68, 0, v68
	v_mul_f32_e32 v64, v64, v64
	v_max_f32_e32 v65, 0, v65
	v_max_f32_e32 v66, 0, v66
	v_max_f32_e32 v67, 0, v67
	v_mul_f32_e32 v68, v68, v68
	v_mul_f32_e32 v65, v65, v65
	v_mul_f32_e32 v66, v66, v66
	v_mul_f32_e32 v67, v67, v67
	v_cvt_pk_bf16_f32 v64, v68, v64
	v_max_f32_e32 v56, 0, v56
	v_max_f32_e32 v57, 0, v57
	v_max_f32_e32 v58, 0, v58
	v_cvt_pk_bf16_f32 v65, v65, v66
	v_cvt_pk_bf16_f32 v66, v72, v69
	v_cvt_pk_bf16_f32 v67, v70, v67
	global_store_dwordx4 v[76:77], v[64:67], off offset:256
	s_nop 1
	v_mul_f32_e32 v64, v56, v56
	v_max_f32_e32 v56, v61, v61
	v_mul_f32_e32 v61, v57, v57
	v_max_f32_e32 v57, v62, v62
	v_mul_f32_e32 v62, v58, v58
	v_max_f32_e32 v58, v63, v63
	v_max_f32_e32 v56, 0, v56
	v_max_f32_e32 v57, 0, v57
	v_max_f32_e32 v58, 0, v58
	v_max_f32_e32 v59, 0, v59
	v_max_f32_e32 v60, 0, v60
	v_mul_f32_e32 v56, v56, v56
	v_mul_f32_e32 v57, v57, v57
	v_mul_f32_e32 v58, v58, v58
	v_mul_f32_e32 v59, v59, v59
	v_mul_f32_e32 v60, v60, v60
	v_cvt_pk_bf16_f32 v56, v60, v56
	v_cvt_pk_bf16_f32 v57, v57, v58
	v_cvt_pk_bf16_f32 v58, v64, v61
	v_cvt_pk_bf16_f32 v59, v62, v59
	v_add_co_u32_e32 v62, vcc, s73, v120
	s_nop 0
	v_addc_co_u32_e32 v63, vcc, 0, v121, vcc
	v_max_f32_e32 v48, 0, v48
	global_store_dwordx4 v[62:63], v[56:59], off
	v_max_f32_e32 v49, 0, v49
	v_max_f32_e32 v50, 0, v50
	v_mul_f32_e32 v56, v48, v48
	v_max_f32_e32 v48, v53, v53
	v_max_f32_e32 v48, 0, v48
	v_mul_f32_e32 v53, v49, v49
	v_max_f32_e32 v49, v54, v54
	v_mul_f32_e32 v54, v50, v50
	v_max_f32_e32 v50, v55, v55
	v_max_f32_e32 v52, 0, v52
	v_mul_f32_e32 v48, v48, v48
	v_max_f32_e32 v49, 0, v49
	v_max_f32_e32 v50, 0, v50
	v_max_f32_e32 v51, 0, v51
	v_lshl_add_u64 v[60:61], v[120:121], 0, s[12:13]
	v_mul_f32_e32 v52, v52, v52
	v_mul_f32_e32 v49, v49, v49
	v_mul_f32_e32 v50, v50, v50
	v_mul_f32_e32 v51, v51, v51
	v_cvt_pk_bf16_f32 v48, v52, v48
	v_max_f32_e32 v40, 0, v40
	v_max_f32_e32 v41, 0, v41
	v_max_f32_e32 v42, 0, v42
	v_cvt_pk_bf16_f32 v49, v49, v50
	v_cvt_pk_bf16_f32 v50, v56, v53
	v_cvt_pk_bf16_f32 v51, v54, v51
	global_store_dwordx4 v[60:61], v[48:51], off offset:256
	s_nop 1
	v_mul_f32_e32 v48, v40, v40
	v_max_f32_e32 v40, v45, v45
	v_mul_f32_e32 v45, v41, v41
	v_max_f32_e32 v41, v46, v46
	v_mul_f32_e32 v46, v42, v42
	v_max_f32_e32 v42, v47, v47
	v_max_f32_e32 v40, 0, v40
	v_max_f32_e32 v41, 0, v41
	v_max_f32_e32 v42, 0, v42
	v_max_f32_e32 v43, 0, v43
	v_max_f32_e32 v44, 0, v44
	v_mul_f32_e32 v40, v40, v40
	v_mul_f32_e32 v41, v41, v41
	v_mul_f32_e32 v42, v42, v42
	v_mul_f32_e32 v43, v43, v43
	v_mul_f32_e32 v44, v44, v44
	v_cvt_pk_bf16_f32 v40, v44, v40
	v_cvt_pk_bf16_f32 v41, v41, v42
	v_cvt_pk_bf16_f32 v42, v48, v45
	v_cvt_pk_bf16_f32 v43, v46, v43
	v_add_co_u32_e32 v46, vcc, s74, v120
	s_nop 0
	v_addc_co_u32_e32 v47, vcc, 0, v121, vcc
	v_max_f32_e32 v32, 0, v32
	global_store_dwordx4 v[46:47], v[40:43], off
	v_max_f32_e32 v33, 0, v33
	v_max_f32_e32 v34, 0, v34
	v_mul_f32_e32 v40, v32, v32
	v_max_f32_e32 v32, v37, v37
	v_max_f32_e32 v32, 0, v32
	v_mul_f32_e32 v37, v33, v33
	v_max_f32_e32 v33, v38, v38
	v_mul_f32_e32 v38, v34, v34
	v_max_f32_e32 v34, v39, v39
	v_max_f32_e32 v36, 0, v36
	v_mul_f32_e32 v32, v32, v32
	v_max_f32_e32 v33, 0, v33
	v_max_f32_e32 v34, 0, v34
	v_max_f32_e32 v35, 0, v35
	v_lshl_add_u64 v[44:45], v[120:121], 0, s[14:15]
	v_mul_f32_e32 v36, v36, v36
	v_mul_f32_e32 v33, v33, v33
	v_mul_f32_e32 v34, v34, v34
	v_mul_f32_e32 v35, v35, v35
	v_cvt_pk_bf16_f32 v32, v36, v32
	v_max_f32_e32 v24, 0, v24
	v_max_f32_e32 v25, 0, v25
	v_max_f32_e32 v26, 0, v26
	v_cvt_pk_bf16_f32 v33, v33, v34
	v_cvt_pk_bf16_f32 v34, v40, v37
	v_cvt_pk_bf16_f32 v35, v38, v35
	global_store_dwordx4 v[44:45], v[32:35], off offset:256
	s_nop 1
	v_mul_f32_e32 v32, v24, v24
	v_max_f32_e32 v24, v29, v29
	v_mul_f32_e32 v29, v25, v25
	v_max_f32_e32 v25, v30, v30
	v_mul_f32_e32 v30, v26, v26
	v_max_f32_e32 v26, v31, v31
	v_max_f32_e32 v24, 0, v24
	v_max_f32_e32 v25, 0, v25
	v_max_f32_e32 v26, 0, v26
	v_max_f32_e32 v27, 0, v27
	v_max_f32_e32 v28, 0, v28
	v_mul_f32_e32 v24, v24, v24
	v_mul_f32_e32 v25, v25, v25
	v_mul_f32_e32 v26, v26, v26
	v_mul_f32_e32 v27, v27, v27
	v_mul_f32_e32 v28, v28, v28
	v_cvt_pk_bf16_f32 v24, v28, v24
	v_cvt_pk_bf16_f32 v25, v25, v26
	v_cvt_pk_bf16_f32 v26, v32, v29
	v_cvt_pk_bf16_f32 v27, v30, v27
	v_add_co_u32_e32 v30, vcc, s75, v120
	s_nop 0
	v_addc_co_u32_e32 v31, vcc, 0, v121, vcc
	v_max_f32_e32 v16, 0, v16
	global_store_dwordx4 v[30:31], v[24:27], off
	v_max_f32_e32 v17, 0, v17
	v_max_f32_e32 v18, 0, v18
	v_mul_f32_e32 v24, v16, v16
	v_max_f32_e32 v16, v21, v21
	v_max_f32_e32 v16, 0, v16
	v_mul_f32_e32 v21, v17, v17
	v_max_f32_e32 v17, v22, v22
	v_mul_f32_e32 v22, v18, v18
	v_max_f32_e32 v18, v23, v23
	v_max_f32_e32 v20, 0, v20
	v_mul_f32_e32 v16, v16, v16
	v_max_f32_e32 v17, 0, v17
	v_max_f32_e32 v18, 0, v18
	v_max_f32_e32 v19, 0, v19
	v_lshl_add_u64 v[28:29], v[120:121], 0, s[16:17]
	v_mul_f32_e32 v20, v20, v20
	v_mul_f32_e32 v17, v17, v17
	v_mul_f32_e32 v18, v18, v18
	v_mul_f32_e32 v19, v19, v19
	v_cvt_pk_bf16_f32 v16, v20, v16
	v_max_f32_e32 v8, 0, v8
	v_max_f32_e32 v9, 0, v9
	v_max_f32_e32 v10, 0, v10
	v_cvt_pk_bf16_f32 v17, v17, v18
	v_cvt_pk_bf16_f32 v18, v24, v21
	v_cvt_pk_bf16_f32 v19, v22, v19
	global_store_dwordx4 v[28:29], v[16:19], off offset:256
	s_nop 1
	v_mul_f32_e32 v16, v8, v8
	v_max_f32_e32 v8, v13, v13
	v_mul_f32_e32 v13, v9, v9
	v_max_f32_e32 v9, v14, v14
	v_mul_f32_e32 v14, v10, v10
	v_max_f32_e32 v10, v15, v15
	v_max_f32_e32 v8, 0, v8
	v_max_f32_e32 v9, 0, v9
	v_max_f32_e32 v10, 0, v10
	v_max_f32_e32 v11, 0, v11
	v_max_f32_e32 v12, 0, v12
	v_mul_f32_e32 v8, v8, v8
	v_mul_f32_e32 v9, v9, v9
	v_mul_f32_e32 v10, v10, v10
	v_mul_f32_e32 v11, v11, v11
	v_mul_f32_e32 v12, v12, v12
	v_cvt_pk_bf16_f32 v8, v12, v8
	v_cvt_pk_bf16_f32 v9, v9, v10
	v_cvt_pk_bf16_f32 v10, v16, v13
	v_cvt_pk_bf16_f32 v11, v14, v11
	v_add_co_u32_e32 v14, vcc, s76, v120
	v_addc_co_u32_e32 v15, vcc, 0, v121, vcc
	v_max_f32_e32 v0, 0, v0
	v_max_f32_e32 v1, 0, v1
	v_max_f32_e32 v2, 0, v2
	global_store_dwordx4 v[14:15], v[8:11], off
	s_nop 1
	v_mul_f32_e32 v8, v0, v0
	v_max_f32_e32 v0, v5, v5
	v_mul_f32_e32 v5, v1, v1
	v_max_f32_e32 v1, v6, v6
	v_mul_f32_e32 v6, v2, v2
	v_max_f32_e32 v2, v7, v7
	v_max_f32_e32 v0, 0, v0
	v_max_f32_e32 v1, 0, v1
	v_max_f32_e32 v2, 0, v2
	v_max_f32_e32 v3, 0, v3
	v_lshl_add_u64 v[12:13], v[120:121], 0, s[18:19]
	v_max_f32_e32 v4, 0, v4
	v_mul_f32_e32 v0, v0, v0
	v_mul_f32_e32 v1, v1, v1
	v_mul_f32_e32 v2, v2, v2
	v_mul_f32_e32 v3, v3, v3
	s_andn2_b64 vcc, exec, s[2:3]
	s_mov_b64 s[2:3], -1
	v_mul_f32_e32 v4, v4, v4
	v_cvt_pk_bf16_f32 v0, v4, v0
	v_cvt_pk_bf16_f32 v1, v1, v2
	v_cvt_pk_bf16_f32 v2, v8, v5
	v_cvt_pk_bf16_f32 v3, v6, v3
	global_store_dwordx4 v[12:13], v[0:3], off offset:256
	s_cbranch_vccnz .LBB0_3055
	s_andn2_b64 vcc, exec, s[4:5]
	s_cbranch_vccnz .LBB0_3054
	s_barrier
	s_branch .LBB0_3054
